# stacked: PEER step A/B gather loops unrolled x2 without copy blocks; mixer-A attention units remapped so the 8 query blocks of a head share an XCD L2; bisect16 count loops tightened
# speedup vs baseline: 1.0319x; 1.0133x over previous
; #define LAS __attribute__((address_space(3)))
; __device__ __forceinline__ float alibi_slope(int h) { return exp2f(-(float)(h + 1)); }
; __device__ __forceinline__ void p2_attention(const Args& a, LAS unsigned char* lds) {
;     ...
;             LAS float* ACC = (LAS float*)lds;
;             LAS float* LS = ACC + 512 * 68;
;             for (int unit = bid; unit < NB * 8 * (SEQ / 512); unit += G) {
;                 const int b = unit >> 6, h = (unit >> 3) & 7, q0 = (unit & 7) * 512;
; #pragma unroll 1
;                 for (int pass = 0; pass < 3; ++pass) {
;                     const int sh = 2 * pass, d = 1 << sh;
; #pragma unroll 1
;                     for (int tt = 0; tt < 16 / NWR; ++tt) {
;                         const int T = aw + NWR * tt;
;                         int res, i0, qlb, qls;
;                         if (pass == 0) { res = 0; i0 = q0 + 32 * T; qlb = 32 * T; qls = 1; }
;                         else if (pass == 1) { res = T >> 2; i0 = (q0 >> 2) + 32 * (T & 3); qlb = 128 * (T & 3) + res; qls = 4; }
;                         else { res = T; i0 = q0 >> 4; qlb = res; qls = 16; }
;                         WT w; w.q = QA + ((size_t)(b * SEQ + res) + (size_t)i0 * d) * 512 + h * 64; w.qstride = (size_t)d * 512;
;                         w.k = KA + ((size_t)(b * SEQ + res)) * 512 + h * 64; w.v = VA + ((size_t)(b * SEQ + res)) * 512 + h * 64; w.kstride = (size_t)d * 512;
;                         w.i0 = i0; w.slope2 = alibi_slope(h) * (float)d * LOG2E;
.LBB0_636:
	s_cmpk_lt_i32 s86, 0x100
	s_cselect_b64 s[14:15], -1, 0
	s_cmpk_gt_i32 s86, 0xff
	s_cbranch_scc1 .LBB0_664
	s_waitcnt lgkmcnt(1)
	v_max_f32_e32 v2, v153, v153
	s_waitcnt lgkmcnt(0)
	v_max_f32_e32 v3, v152, v152
	v_max_f32_e32 v2, v3, v2
	v_mul_f32_e32 v2, 0x41000000, v2
	v_mul_f32_e32 v152, 0x3f8147ae, v2
	v_and_b32_e32 v2, 8, v144
	v_mov_b32_e32 v129, 0
	v_lshlrev_b32_e32 v128, 1, v2
	s_add_u32 s17, s24, 0x5dc6000
	v_lshl_add_u64 v[4:5], s[24:25], 0, v[128:129]
	s_mov_b64 s[0:1], 0x4cc6000
	s_addc_u32 s18, s25, 0
	v_lshl_add_u64 v[130:131], v[4:5], 0, s[0:1]
	v_and_b32_e32 v3, 4, v148
	v_and_b32_e32 v4, 8, v149
	s_bfe_u32 s0, s3, 0x20006
	v_and_b32_e32 v128, 0x60, v146
	v_or3_b32 v153, v3, v143, v4
	s_lshl_b32 s19, s0, 5
	s_lshl_b32 s20, s0, 7
	v_lshlrev_b32_e32 v3, 4, v0
	v_lshl_add_u64 v[4:5], s[24:25], 0, v[128:129]
	s_mov_b64 s[0:1], 0x6ec6000
	v_lshlrev_b32_e32 v6, 2, v0
	v_lshl_add_u64 v[132:133], v[4:5], 0, s[0:1]
	v_and_b32_e32 v4, 0x400, v147
	v_and_b32_e32 v5, 0x3c0, v3
	v_and_b32_e32 v3, 0x2c0, v3
	v_and_or_b32 v6, v6, 12, v145
	v_add3_u32 v4, s21, v4, v5
	v_and_b32_e32 v5, 32, v146
	v_add_u32_e32 v3, s21, v3
	v_lshlrev_b32_e32 v6, 1, v6
	v_lshlrev_b32_e32 v128, 3, v142
	v_sub_u32_e32 v7, v151, v2
	v_bfe_u32 v154, v0, 2, 4
	s_mov_b32 s11, 0
	v_lshl_add_u32 v155, v142, 4, 0
	v_lshl_add_u64 v[134:135], s[6:7], 0, v[128:129]
	v_cmp_gt_u32_e64 s[4:5], 32, v1
	v_or_b32_e32 v156, 0xffffff80, v2
	v_add_u32_e32 v157, 0x69, v7
	s_mov_b32 s21, 0x42fc0000
	v_mov_b32_e32 v158, 0x42800000
	s_mov_b32 s22, 0xf800000
	v_mov_b32_e32 v159, 0x260
	v_lshlrev_b32_e32 v136, 1, v2
	s_movk_i32 s23, 0x81
	s_movk_i32 s33, 0xffef
	s_movk_i32 s48, 0xffee
	s_movk_i32 s49, 0xffed
	s_movk_i32 s50, 0xffec
	s_movk_i32 s51, 0xffeb
	s_movk_i32 s52, 0xffea
	s_movk_i32 s53, 0xffe9
	s_movk_i32 s56, 0xffe8
	v_add_u32_e32 v160, v4, v5
	v_add_u32_e32 v161, v3, v6
	s_movk_i32 s57, 0x110
	s_mov_b32 s68, s86
	s_cmpk_lg_i32 s2, 0x100
	s_cbranch_scc1 .Lp2_noremap
	s_and_b32 s68, s86, 7
	s_lshl_b32 s68, s68, 2
	s_lshr_b32 s0, s86, 6
	s_add_i32 s68, s68, s0
	s_lshl_b32 s68, s68, 3
	s_lshr_b32 s0, s86, 3
	s_and_b32 s0, s0, 7
	s_or_b32 s68, s68, s0
.Lp2_noremap:
	s_branch .LBB0_639
